# P6 CU split: WGs<128 do all prompt-attention items, WGs>=128 stream sample attention + state scan; coalesced sk_tile in P2
# speedup vs baseline: 1.0255x; 1.0116x over previous
; #define LAS __attribute__((address_space(3)))
; __device__ __forceinline__ void ret_upd_phase(LAS unsigned char* lds, const bf16* __restrict__ QKVb, float* __restrict__ UPD, unsigned* cnt, int tid, int wave, int lane) {
;     constexpr int RSV = 272, RSK = 144, GRP = 128 * RSV + 128 * RSK;
;     const int grp = wave >> 2, dt = wave & 3;
;     LAS unsigned char* vb = lds + grp * GRP;
;     LAS unsigned char* kb = vb + 128 * RSV;
;     const int i = lane & 31, hh = lane >> 5, i16 = lane & 15, tq = i16 >> 2, tp = i16 & 3, blk = (lane >> 4) & 1;
;     for (int it = blockIdx.x; it < 256; it += gridDim.x) {
;         const int item = it * 2 + grp, n = item >> 2, h = item & 3;
;         const float lg2 = log_g(h) * 1.4426950408889634f;
;         const int t4 = tid & 255;
; __global__ void __launch_bounds__(NTHR, 2) mk_fwd(Args a) {
;     ...
;     unsigned* const ctlw = (unsigned*)(ws + WS_CTL);
;     const bool upd_late = (blockIdx.x & 8) != 0;
;     if (!upd_late) ret_upd_phase(lds, P.QKVb, P.UPD, ctlw + CW_UPD, tid, wave, lane);
.LBB0_949:
	s_or_b64 exec, exec, s[0:1]
	s_add_u32 s36, s90, 0x21700000
	s_addc_u32 s37, s91, 0
	s_mov_b64 s[24:25], 0
	s_nop 0
	s_and_b64 vcc, exec, s[24:25]
	s_waitcnt lgkmcnt(0)
	s_barrier
	s_cbranch_vccnz .LBB0_961
	s_and_b64 vcc, exec, s[52:53]
	s_cbranch_vccnz .LBB0_961
	s_add_u32 s0, s90, 0x10000
	v_readlane_b32 s5, v254, 0
	s_addc_u32 s1, s91, 0
	s_lshr_b32 s2, s5, 8
	v_bfe_u32 v4, v0, 2, 2
	v_lshrrev_b32_e32 v6, 5, v162
	s_bfe_u32 s5, s5, 0x20006
	v_and_b32_e32 v3, 16, v0
	s_mul_i32 s4, s2, 0xd000
	v_lshl_or_b32 v9, v6, 3, v4
	s_lshl_b32 s6, s5, 5
	v_and_b32_e32 v4, 12, v163
	s_add_i32 s4, s4, 0
	v_or3_b32 v10, s6, v3, v4
	v_or_b32_e32 v3, v4, v3
	v_lshl_add_u32 v7, v167, 4, s4
	v_lshl_add_u32 v8, v1, 4, s4
	v_lshl_add_u32 v10, v10, 1, s4
	v_lshl_add_u32 v3, v3, 1, s4
	s_lshl_b32 s4, s5, 13
	v_and_b32_e32 v5, 31, v0
	s_add_u32 s4, s36, s4
	s_waitcnt vmcnt(2)
	v_mov_b32_e32 v35, 0
	s_addc_u32 s5, s37, 0
	v_lshlrev_b32_e32 v34, 2, v5
	v_lshl_add_u64 v[4:5], s[4:5], 0, v[34:35]
	s_movk_i32 s4, 0x100
	v_or_b32_sdwa v12, v0, s4 dst_sel:DWORD dst_unused:UNUSED_PAD src0_sel:BYTE_0 src1_sel:DWORD
	s_movk_i32 s4, 0x200
	v_or_b32_sdwa v14, v0, s4 dst_sel:DWORD dst_unused:UNUSED_PAD src0_sel:BYTE_0 src1_sel:DWORD
	v_or_b32_e32 v16, 0x300, v0
	v_bfe_u32 v50, v0, 3, 5
	v_lshrrev_b32_e32 v52, 3, v12
	v_lshrrev_b32_e32 v54, 3, v14
	v_lshrrev_b32_e32 v56, 3, v16
	v_bfe_u32 v42, v0, 4, 4
	v_lshrrev_b32_e32 v43, 4, v12
	v_lshrrev_b32_e32 v44, 4, v14
	v_lshrrev_b32_e32 v45, 4, v16
	v_or_b32_e32 v49, 0x70, v186
	v_xor_b32_e32 v19, 0x7f, v50
	v_xor_b32_e32 v12, 0x7f, v52
	v_xor_b32_e32 v14, 0x7f, v54
	v_xor_b32_e32 v16, 0x7f, v56
	s_lshl_b32 s4, s86, 1
	v_lshlrev_b32_e32 v2, 3, v1
	v_mul_u32_u24_e32 v11, 0x110, v42
	v_mul_u32_u24_e32 v13, 0x110, v43
	v_mul_u32_u24_e32 v15, 0x110, v44
	v_mul_u32_u24_e32 v17, 0x110, v45
	v_mul_u32_u24_e32 v18, 0x110, v49
	v_cvt_f32_ubyte0_e32 v51, v19
	v_mul_u32_u24_e32 v19, 0x90, v50
	v_cvt_f32_ubyte0_e32 v53, v12
	v_mul_u32_u24_e32 v12, 0x90, v52
	v_cvt_f32_ubyte0_e32 v55, v14
	v_mul_u32_u24_e32 v14, 0x90, v54
	v_cvt_f32_ubyte0_e32 v57, v16
	v_mul_u32_u24_e32 v16, 0x90, v56
	v_mul_u32_u24_e32 v20, 0x110, v9
	v_mul_u32_u24_e32 v9, 0x90, v9
	v_lshlrev_b32_e32 v34, 10, v6
	s_add_i32 s4, s2, s4
	s_lshl_b32 s5, s86, 6
	s_lshl_b32 s2, s2, 5
	s_mov_b32 s3, 0
	v_or_b32_e32 v46, 64, v42
	v_or_b32_e32 v47, 0x50, v42
	v_or_b32_e32 v48, 0x60, v42
	v_lshl_add_u64 v[36:37], v[4:5], 0, v[34:35]
	s_lshl_b32 s10, s87, 1
	s_add_i32 s11, s5, s2
	s_lshl_b32 s12, s87, 6
	s_movk_i32 s13, 0x1800
	v_mov_b64_e32 v[38:39], s[72:73]
	v_lshlrev_b32_e32 v34, 1, v134
	s_movk_i32 s14, 0x1000
	v_add_u32_e32 v58, v7, v11
	v_add_u32_e32 v59, v7, v13
	v_add_u32_e32 v60, v7, v15
	v_add_u32_e32 v61, v7, v17
	v_add_u32_e32 v62, v7, v18
	v_lshlrev_b32_e32 v40, 1, v2
	v_mov_b32_e32 v41, v35
	v_add_u32_e32 v63, v8, v19
	v_add_u32_e32 v64, v8, v12
	v_add_u32_e32 v65, v8, v14
	v_add_u32_e32 v66, v8, v16
	v_add_u32_e32 v67, v10, v20
	v_add_u32_e32 v68, v3, v9
	v_mov_b32_e32 v69, 0xbbb906ce
	v_mov_b32_e32 v70, 0xbc3963dd
	s_mov_b32 s15, s86
	s_branch .LBB0_953

; __device__ __forceinline__ void attn_mfma_phase(LAS unsigned char* lds, const bf16* QKVb, bf16* OPART, float2* ML, int tid, int wave, int lane) {
;     ...
;     auto decode = [](int item, int& h, int& b, int& r, int& bk) { h = item / 192; const int w = item % 192;
;         if (w < 64) { b = 0; r = 0; bk = w; } else if (w < 128) { b = 1; r = (w - 64) >> 4; bk = (w - 64) & 15; } else { b = 2; r = (w - 128) >> 2; bk = (w - 128) & 3; } };
;     auto issue = [&](int item) { int h, b, r, bk; decode(item, h, b, r, bk); const int d = 1 << (2 * b), L0 = bk * 256;
; #pragma unroll
;         for (int c = 0; c < 6; ++c) { const int e = tid + NTHR * c, j = e >> 3, ch = e & 7, l = L0 - 128 + j;
;             if (l >= 0) { const bf16* src = QKVb + (size_t)(l * d + r) * INW + h * 64 + 8 * ch; pk[c] = *(const v4u*)(src + C_KA); pv[c] = *(const v4u*)(src + C_VA); } } };
;     if ((int)blockIdx.x < 1536) issue(blockIdx.x);
;     for (int item = blockIdx.x; item < 1536; item += gridDim.x) {
;         int h, b, r, bk; decode(item, h, b, r, bk);
;         const int d = 1 << (2 * b), L0 = bk * 256;
.LBB0_986:
	s_cmpk_ge_i32 s86, 128
	s_cselect_b32 s86, 0x600, s86
	s_cmpk_lt_i32 s86, 0x600
	s_cselect_b64 s[0:1], -1, 0
	s_cmpk_gt_i32 s86, 0x5ff
	s_cbranch_scc1 .LBB0_1008
	s_mul_hi_i32 s2, s86, 0x2aaaaaab
	s_lshr_b32 s3, s2, 31
	s_ashr_i32 s6, s2, 5
	s_add_i32 s6, s6, s3
	s_mul_i32 s2, s6, 0xc0
	s_sub_i32 s7, s86, s2
	s_cmp_lt_i32 s7, 64
	s_mov_b32 s2, 0
	s_cbranch_scc1 .LBB0_990
	s_cmpk_gt_u32 s7, 0x7f
	s_cbranch_scc0 .LBB0_991
	s_add_i32 s2, s7, 0xffffff80
	s_lshr_b32 s2, s2, 2
	s_and_b32 s8, s7, 3
	s_mov_b32 s3, 4
	s_cbranch_execz .LBB0_992
	s_branch .LBB0_993

; #define LAS __attribute__((address_space(3)))
; __device__ __forceinline__ void attn_mfma_phase(LAS unsigned char* lds, const bf16* QKVb, bf16* OPART, float2* ML, int tid, int wave, int lane) {
;     ...
;     for (int item = blockIdx.x; item < 1536; item += gridDim.x) {
;         int h, b, r, bk; decode(item, h, b, r, bk);
;         const int d = 1 << (2 * b), L0 = bk * 256;
; #pragma unroll
;         for (int c = 0; c < 6; ++c) { const int e = tid + NTHR * c, j = e >> 3, ch = e & 7;
;             *(LAS v4u*)(kimg + j * RSK + 16 * ch) = pk[c]; *(LAS v4u*)(vimg + j * RSV + 16 * ch) = pv[c]; }
;         const int l0 = L0 + 32 * wave;
;         const int tok_q = (l0 + i) * d + r;
;         const bf16* qp = QKVb + (size_t)tok_q * INW + C_QA + h * 64 + 8 * hh;
;         bf16x8 qf[4];
; #pragma unroll
;         for (int ks = 0; ks < 4; ++ks) qf[ks] = *(const bf16x8*)(qp + 16 * ks);
;         __syncthreads();
;         if (item + (int)gridDim.x < 1536) issue(item + gridDim.x);
.LBB0_1018:
	s_lshl_b32 s87, s84, 8
	s_add_i32 s87, s87, s2
	s_lshl_b32 s70, s1, 1
	v_or_b32_e32 v2, s87, v133
	v_lshlrev_b32_e32 v2, s70, v2
	v_readlane_b32 s70, v254, 55
	v_readlane_b32 s71, v254, 56
	v_add_u32_e32 v148, s33, v2
	s_lshl_b32 s94, s0, 6
	v_mov_b64_e32 v[2:3], s[70:71]
	v_mad_i64_i32 v[2:3], s[70:71], v148, s3, v[2:3]
	s_ashr_i32 s95, s94, 31
	v_lshl_add_u64 v[2:3], s[94:95], 1, v[2:3]
	v_lshl_add_u64 v[2:3], v[2:3], 0, v[142:143]
	global_load_dwordx4 v[114:117], v[2:3], off
	global_load_dwordx4 v[118:121], v[2:3], off offset:32
	global_load_dwordx4 v[122:125], v[2:3], off offset:64
	global_load_dwordx4 v[126:129], v[2:3], off offset:96
	s_movk_i32 s33, 128
	s_add_i32 s86, s86, s33
	s_cmpk_gt_i32 s86, 0x5ff
	s_cselect_b64 s[72:73], -1, 0
	v_add_u32_e32 v2, v135, v155
	s_and_b64 vcc, exec, s[72:73]
	s_waitcnt vmcnt(5)
	ds_write_b128 v159, v[70:73]
	s_waitcnt vmcnt(4)
	ds_write_b128 v2, v[66:69] offset:55296
	ds_write_b128 v160, v[78:81]
	ds_write_b128 v161, v[74:77] offset:55296
	ds_write_b128 v159, v[86:89] offset:18432
	ds_write_b128 v168, v[82:85] offset:55296
	ds_write_b128 v169, v[94:97]
	ds_write_b128 v170, v[90:93] offset:55296
	ds_write_b128 v159, v[102:105] offset:36864
	ds_write_b128 v171, v[98:101] offset:55296
	ds_write_b128 v172, v[110:113]
	ds_write_b128 v173, v[106:109] offset:55296
	s_waitcnt lgkmcnt(0)
	s_barrier
	s_cbranch_vccnz .LBB0_1039
	s_mul_hi_i32 s33, s86, 0x2aaaaaab
	s_lshr_b32 s70, s33, 31
	s_ashr_i32 s96, s33, 5
	s_add_i32 s96, s96, s70
	s_mul_i32 s33, s96, 0xc0
	s_sub_i32 s70, s86, s33
	s_cmp_lt_i32 s70, 64
	s_mov_b32 s84, 0
	s_cbranch_scc1 .LBB0_1025
	s_cmpk_gt_u32 s70, 0x7f
	s_mov_b64 s[92:93], -1
	s_cbranch_scc0 .LBB0_1022
	s_add_i32 s33, s70, 0xffffff80
	s_lshr_b32 s84, s33, 2
	s_and_b32 s33, s70, 3
	s_mov_b64 s[92:93], 0

; #define LAS __attribute__((address_space(3)))
; __device__ __forceinline__ void ret_upd_phase(LAS unsigned char* lds, const bf16* __restrict__ QKVb, float* __restrict__ UPD, unsigned* cnt, int tid, int wave, int lane) {
;     constexpr int RSV = 272, RSK = 144, GRP = 128 * RSV + 128 * RSK;
;     const int grp = wave >> 2, dt = wave & 3;
;     LAS unsigned char* vb = lds + grp * GRP;
;     LAS unsigned char* kb = vb + 128 * RSV;
;     const int i = lane & 31, hh = lane >> 5, i16 = lane & 15, tq = i16 >> 2, tp = i16 & 3, blk = (lane >> 4) & 1;
;     for (int it = blockIdx.x; it < 256; it += gridDim.x) {
;         const int item = it * 2 + grp, n = item >> 2, h = item & 3;
;         const float lg2 = log_g(h) * 1.4426950408889634f;
;         const int t4 = tid & 255;
; __global__ void __launch_bounds__(NTHR, 2) mk_fwd(Args a) {
;     ...
;     const bool upd_late = (blockIdx.x & 8) != 0;
;     if (!upd_late) ret_upd_phase(lds, P.QKVb, P.UPD, ctlw + CW_UPD, tid, wave, lane);
;     ret_sample_phase(lds, P.QKVb, P.st, P.gnw, P.MIX, P.out, tid);
;     attn_mfma_phase(lds, P.QKVb, P.OPART, P.ML, tid, wave, lane);
;     if (upd_late) ret_upd_phase(lds, P.QKVb, P.UPD, ctlw + CW_UPD, tid, wave, lane);
.LBB0_1055:
	v_readlane_b32 s86, v254, 11
	s_nop 3
	s_andn2_b64 vcc, exec, s[24:25]
	s_cbranch_vccnz .LBB0_1067
	s_and_b64 vcc, exec, s[52:53]
	s_cbranch_vccnz .LBB0_1067
	s_add_u32 s0, s90, 0x10000
	v_readlane_b32 s3, v254, 0
	s_addc_u32 s1, s91, 0
	s_lshr_b32 s4, s3, 8
	s_bfe_u32 s3, s3, 0x20006
	v_and_b32_e32 v3, 16, v0
	s_mul_i32 s2, s4, 0xd000
	s_lshl_b32 s6, s3, 5
	v_and_b32_e32 v4, 12, v163
	s_add_i32 s2, s2, 0
	v_or3_b32 v5, s6, v3, v4
	v_or_b32_e32 v3, v4, v3
	v_lshl_add_u32 v6, v167, 4, s2
	v_lshl_add_u32 v7, v1, 4, s2
	v_lshl_add_u32 v9, v5, 1, s2
	v_lshl_add_u32 v3, v3, 1, s2
	s_lshl_b32 s2, s3, 13
	s_add_u32 s2, s36, s2
	s_waitcnt vmcnt(2)
	v_mov_b32_e32 v35, 0
	s_addc_u32 s3, s37, 0
	v_lshlrev_b32_e32 v34, 2, v133
	v_lshl_add_u64 v[4:5], s[2:3], 0, v[34:35]
	s_movk_i32 s2, 0x100
	v_or_b32_sdwa v11, v0, s2 dst_sel:DWORD dst_unused:UNUSED_PAD src0_sel:BYTE_0 src1_sel:DWORD
	s_movk_i32 s2, 0x200
	v_or_b32_sdwa v13, v0, s2 dst_sel:DWORD dst_unused:UNUSED_PAD src0_sel:BYTE_0 src1_sel:DWORD
	v_or_b32_e32 v15, 0x300, v0
	v_bfe_u32 v50, v0, 3, 5
	v_lshrrev_b32_e32 v52, 3, v11
	v_lshrrev_b32_e32 v54, 3, v13
	v_lshrrev_b32_e32 v56, 3, v15
	v_lshl_or_b32 v8, v191, 3, v192
	v_bfe_u32 v42, v0, 4, 4
	v_lshrrev_b32_e32 v43, 4, v11
	v_lshrrev_b32_e32 v44, 4, v13
	v_lshrrev_b32_e32 v45, 4, v15
	v_or_b32_e32 v49, 0x70, v186
	v_xor_b32_e32 v18, 0x7f, v50
	v_xor_b32_e32 v11, 0x7f, v52
	v_xor_b32_e32 v13, 0x7f, v54
	v_xor_b32_e32 v15, 0x7f, v56
	s_lshl_b32 s2, s86, 1
	v_readlane_b32 s8, v254, 55
	v_lshlrev_b32_e32 v2, 3, v1
	v_mul_u32_u24_e32 v10, 0x110, v42
	v_mul_u32_u24_e32 v12, 0x110, v43
	v_mul_u32_u24_e32 v14, 0x110, v44
	v_mul_u32_u24_e32 v16, 0x110, v45
	v_mul_u32_u24_e32 v17, 0x110, v49
	v_cvt_f32_ubyte0_e32 v51, v18
	v_mul_u32_u24_e32 v18, 0x90, v50
	v_cvt_f32_ubyte0_e32 v53, v11
	v_mul_u32_u24_e32 v11, 0x90, v52
	v_cvt_f32_ubyte0_e32 v55, v13
	v_mul_u32_u24_e32 v13, 0x90, v54
	v_cvt_f32_ubyte0_e32 v57, v15
	v_mul_u32_u24_e32 v15, 0x90, v56
	v_mul_u32_u24_e32 v19, 0x110, v8
	v_mul_u32_u24_e32 v8, 0x90, v8
	v_lshlrev_b32_e32 v34, 10, v191
	s_add_i32 s6, s4, s2
	s_lshl_b32 s3, s86, 6
	s_lshl_b32 s4, s4, 5
	v_readlane_b32 s9, v254, 56
	s_mov_b32 s5, 0
	v_or_b32_e32 v46, 64, v42
	v_or_b32_e32 v47, 0x50, v42
	v_or_b32_e32 v48, 0x60, v42
	v_lshl_add_u64 v[36:37], v[4:5], 0, v[34:35]
	s_lshl_b32 s2, s87, 1
	s_add_i32 s3, s3, s4
	s_lshl_b32 s12, s87, 6
	s_movk_i32 s13, 0x1800
	v_mov_b64_e32 v[38:39], s[8:9]
	v_lshlrev_b32_e32 v34, 1, v134
	s_movk_i32 s14, 0x1000
	v_add_u32_e32 v58, v6, v10
	v_add_u32_e32 v59, v6, v12
	v_add_u32_e32 v60, v6, v14
	v_add_u32_e32 v61, v6, v16
	v_add_u32_e32 v62, v6, v17
	v_lshlrev_b32_e32 v40, 1, v2
	v_mov_b32_e32 v41, v35
	v_add_u32_e32 v63, v7, v18
	v_add_u32_e32 v64, v7, v11
	v_add_u32_e32 v65, v7, v13
	s_waitcnt vmcnt(0)
	v_add_u32_e32 v66, v7, v15
	v_add_u32_e32 v67, v9, v19
	v_add_u32_e32 v68, v3, v8
	v_mov_b32_e32 v69, 0xbbb906ce
	v_mov_b32_e32 v70, 0xbc3963dd
	s_mov_b32 s15, s86
	s_branch .LBB0_1059

; __device__ __forceinline__ void attn_sample_phase(const bf16* QKVb, const float* ck, const float* cv, const float* out, bf16* SPART, float2* SML, int gw, int NGW, int lane) {
;     const int l16 = lane & 15, hq = lane >> 4;
;     for (int item = gw; item < DBATCH * SA_CH; item += NGW) {
; __global__ void __launch_bounds__(NTHR, 2) mk_fwd(Args a) {
;     ...
;     {
;         const int NI = NGW - DBATCH * SA_CH;
;         if (NI > 0 && NI <= G) {
;             const int bx = (int)blockIdx.x;
;             if (bx < NI && wave == NWAVES - 1) { ret_upd_wait_wave(ctlw + CW_UPD, ctlw + CW_TMO, lane); ret_scan_phase(P.UPD, P.SPT, P.out, bx * 64 + lane, NI * 64); }
;             else attn_sample_phase(P.QKVb, P.ck, P.cv, P.out, P.SPART, P.SML, bx < NI ? bx * (NWAVES - 1) + wave : NI * (NWAVES - 1) + (bx - NI) * NWAVES + wave, 1 << 20, lane);
;         } else {
;             ret_upd_wait(lds, ctlw + CW_UPD, ctlw + CW_TMO, tid, wave, lane);
;             ret_scan_phase(P.UPD, P.SPT, P.out, tid < 128 ? (int)blockIdx.x * 128 + tid : -1, G * 128);
;             attn_sample_phase(P.QKVb, P.ck, P.cv, P.out, P.SPART, P.SML, gw, NGW, lane);
;         }
.LBB0_1067:
	s_add_u32 s14, s90, 0x2d000000
	s_addc_u32 s15, s91, 0
	s_add_u32 s16, s90, 0x2e000000
	s_addc_u32 s17, s91, 0
	s_add_i32 s18, s69, 0xfffff880
	s_max_i32 s0, s18, 0xf1
	s_cmp_gt_i32 s0, s87
	s_mov_b64 s[0:1], -1
	s_cbranch_scc1 .LBB0_1177
	s_cmpk_lt_i32 s86, 128
	s_cbranch_scc1 .LBB0_1176
	v_readlane_b32 s4, v254, 34
	s_nop 3
	s_sub_i32 s0, s86, 128
	s_lshl_b32 s0, s0, 3
	s_add_i32 s0, s0, s4
	s_mov_b32 s99, s0
	s_cmpk_lt_i32 s0, 0x380
	s_mov_b64 s[4:5], -1
	s_cbranch_scc0 .LBB0_1151
.Lsa_entry:
	s_cmpk_gt_i32 s0, 0x77f
	s_cbranch_scc1 .LBB0_1150
	v_mov_b32_e32 v2, 0
	v_readlane_b32 s2, v254, 55
	s_add_u32 s19, s88, 0x4a20000
	s_waitcnt vmcnt(0)
	v_lshrrev_b32_e32 v100, 4, v162
	v_mov_b32_e32 v135, v2
	v_readlane_b32 s3, v254, 56
	s_addc_u32 s20, s89, 0
	s_add_u32 s21, s88, 0x4b20000
	v_lshl_add_u64 v[4:5], s[2:3], 0, v[134:135]
	v_lshlrev_b32_e32 v6, 7, v100
	v_mov_b32_e32 v7, v2
	v_lshlrev_b32_e32 v102, 2, v162
	s_addc_u32 s22, s89, 0
	v_lshl_add_u64 v[104:105], s[14:15], 0, v[134:135]
	v_cmp_ne_u32_e64 s[4:5], 0, v167
	v_lshl_add_u64 v[106:107], v[4:5], 0, v[6:7]
	v_mov_b32_e32 v101, 0x1800
	s_branch .LBB0_1076
.LBB0_1075:
	s_or_b64 exec, exec, s[6:7]
	s_addk_i32 s0, 0x400
	s_cmpk_gt_i32 s0, 0x77f
	s_nop 0
	s_cbranch_scc1 .LBB0_1150

; __device__ __forceinline__ void ret_scan_phase(const float* __restrict__ UPDT, bf16* __restrict__ SPT, float* __restrict__ out, int first, int stride) {
;     if (first >= 0)
;     for (int e = first; e < 32768; e += stride) {
;         const int h = e >> 13, dv = (e >> 6) & 127, dk = e & 63;
;         const float G = expf(128.f * log_g(h));
;         float S = 0.f;
;         {
;             auto ldb = [&](int n0, float (&u)[16]) {
; #pragma unroll
;                 for (int k = 0; k < 16; ++k) u[k] = UPDT[(size_t)(n0 + k) * 32768 + e]; };
.LBB0_1162:
	s_waitcnt vmcnt(0) lgkmcnt(0)
	buffer_inv sc1
	s_waitcnt vmcnt(0)
	s_sub_i32 s1, s99, 0x380
	s_lshl_b32 s1, s1, 6
	s_cmpk_gt_u32 s1, 0x7fff
	s_movk_i32 s2, 0x7fff
	s_cbranch_scc1 .Lscan_done
	s_lshl_b32 s0, s18, 6
	v_add_u32_e32 v6, s1, v162
	v_or_b32_e32 v2, s1, v162
	v_ashrrev_i32_e32 v7, 31, v6
	s_ashr_i32 s1, s0, 31
	v_lshlrev_b64 v[4:5], 1, v[6:7]
	s_lshl_b64 s[4:5], s[0:1], 1
	v_lshlrev_b64 v[6:7], 2, v[6:7]
	s_lshl_b64 s[8:9], s[0:1], 2
	s_mov_b64 s[6:7], 0
	s_mov_b32 s11, 0
	s_mov_b32 s1, 0x22870000
	s_mov_b32 s3, 0x22880000
	s_mov_b32 s26, 0x22890000
	s_mov_b32 s27, 0x228a0000
	s_mov_b32 s28, 0x228b0000
	s_mov_b32 s29, 0x228c0000
	s_mov_b32 s30, 0x228d0000
	s_mov_b64 s[12:13], 0x200000
	s_mov_b64 s[18:19], 0x400000
	v_mov_b32_e32 v9, 0
	v_mov_b32_e32 v18, 0x3f1b1eb1
	v_mov_b32_e32 v19, 0x3ebb9db9

; __global__ void __launch_bounds__(NTHR, 2) mk_fwd(Args a) {
;     ...
;             if (bx < NI && wave == NWAVES - 1) { ret_upd_wait_wave(ctlw + CW_UPD, ctlw + CW_TMO, lane); ret_scan_phase(P.UPD, P.SPT, P.out, bx * 64 + lane, NI * 64); }
;             else attn_sample_phase(P.QKVb, P.ck, P.cv, P.out, P.SPART, P.SML, bx < NI ? bx * (NWAVES - 1) + wave : NI * (NWAVES - 1) + (bx - NI) * NWAVES + wave, 1 << 20, lane);
.Lscan_done:
	s_mov_b32 s0, s99
	s_branch .Lsa_entry
